# P0->R1 grid barrier split: census + arrive after the modulation GEMV and tables, weight transposes run, wait+acquire before R1
# speedup vs baseline: 1.0094x; 1.0025x over previous
.LBB0_76:
	s_or_b64 exec, exec, s[8:9]
	s_waitcnt vmcnt(0) lgkmcnt(0)
	s_barrier
	s_mov_b64 s[4:5], exec
	v_readlane_b32 s6, v254, 2
	v_readlane_b32 s7, v254, 3
	s_nop 1
	s_and_b64 s[6:7], s[4:5], s[6:7]
	s_mov_b64 exec, s[6:7]
	s_cbranch_execz .Lp0_arrive_join
	s_mov_b64 exec, 0xffff
	v_lshlrev_b32_e32 v1, 8, v191
	s_add_u32 s10, s62, 0x400400
	s_addc_u32 s11, s63, 0
	s_mov_b32 s9, 0
.Lp0_census:
	global_load_dword v2, v1, s[10:11] sc1
	s_waitcnt vmcnt(0)
	s_mov_b32 s12, 0
	s_mov_b32 s13, 0
	v_readlane_b32 s14, v2, 0
	s_add_u32 s12, s12, s14
	s_cmp_lg_u32 s14, 0
	s_addc_u32 s13, s13, 0
	v_readlane_b32 s14, v2, 1
	s_add_u32 s12, s12, s14
	s_cmp_lg_u32 s14, 0
	s_addc_u32 s13, s13, 0
	v_readlane_b32 s14, v2, 2
	s_add_u32 s12, s12, s14
	s_cmp_lg_u32 s14, 0
	s_addc_u32 s13, s13, 0
	v_readlane_b32 s14, v2, 3
	s_add_u32 s12, s12, s14
	s_cmp_lg_u32 s14, 0
	s_addc_u32 s13, s13, 0
	v_readlane_b32 s14, v2, 4
	s_add_u32 s12, s12, s14
	s_cmp_lg_u32 s14, 0
	s_addc_u32 s13, s13, 0
	v_readlane_b32 s14, v2, 5
	s_add_u32 s12, s12, s14
	s_cmp_lg_u32 s14, 0
	s_addc_u32 s13, s13, 0
	v_readlane_b32 s14, v2, 6
	s_add_u32 s12, s12, s14
	s_cmp_lg_u32 s14, 0
	s_addc_u32 s13, s13, 0
	v_readlane_b32 s14, v2, 7
	s_add_u32 s12, s12, s14
	s_cmp_lg_u32 s14, 0
	s_addc_u32 s13, s13, 0
	v_readlane_b32 s14, v2, 8
	s_add_u32 s12, s12, s14
	s_cmp_lg_u32 s14, 0
	s_addc_u32 s13, s13, 0
	v_readlane_b32 s14, v2, 9
	s_add_u32 s12, s12, s14
	s_cmp_lg_u32 s14, 0
	s_addc_u32 s13, s13, 0
	v_readlane_b32 s14, v2, 10
	s_add_u32 s12, s12, s14
	s_cmp_lg_u32 s14, 0
	s_addc_u32 s13, s13, 0
	v_readlane_b32 s14, v2, 11
	s_add_u32 s12, s12, s14
	s_cmp_lg_u32 s14, 0
	s_addc_u32 s13, s13, 0
	v_readlane_b32 s14, v2, 12
	s_add_u32 s12, s12, s14
	s_cmp_lg_u32 s14, 0
	s_addc_u32 s13, s13, 0
	v_readlane_b32 s14, v2, 13
	s_add_u32 s12, s12, s14
	s_cmp_lg_u32 s14, 0
	s_addc_u32 s13, s13, 0
	v_readlane_b32 s14, v2, 14
	s_add_u32 s12, s12, s14
	s_cmp_lg_u32 s14, 0
	s_addc_u32 s13, s13, 0
	v_readlane_b32 s14, v2, 15
	s_add_u32 s12, s12, s14
	s_cmp_lg_u32 s14, 0
	s_addc_u32 s13, s13, 0
	s_cmp_eq_u32 s12, s33
	s_cbranch_scc1 .Lp0_census_done
	s_sleep 1
	s_add_u32 s9, s9, 1
	s_cmp_lt_u32 s9, 0x100000
	s_cbranch_scc1 .Lp0_census
.Lp0_census_done:
	s_getreg_b32 s8, hwreg(HW_REG_XCC_ID, 0, 4)
	s_nop 3
	v_readlane_b32 s14, v2, s8
	s_max_u32 s14, s14, 1
	s_max_u32 s13, s13, 1
	s_mov_b64 exec, 1
	v_mov_b32_e32 v3, 0x23fc0
	v_mov_b32_e32 v4, s14
	v_mov_b32_e32 v5, s13
	ds_write_b64 v3, v[4:5]
	s_lshl_b32 s8, s8, 6
	s_add_u32 s10, s62, 0x40d800
	s_addc_u32 s11, s63, 0
	v_mov_b32_e32 v1, s8
	v_mov_b32_e32 v3, 1
	global_atomic_add v2, v1, v3, s[10:11] sc0
	s_waitcnt vmcnt(0) lgkmcnt(0)
	v_add_u32_e32 v2, 1, v2
	v_cmp_eq_u32_e32 vcc, v2, v4
	s_cbranch_vccz .Lp0_arrive_join
	buffer_wbl2 sc1
	s_waitcnt vmcnt(0)
	v_mov_b32_e32 v1, 0x400
	global_atomic_add v1, v3, s[10:11]
.Lp0_arrive_join:
	s_mov_b64 exec, s[4:5]
	s_cmpk_lg_i32 s33, 0x100
	s_cbranch_scc0 .LBB0_78
	s_abs_i32 s0, s33
	v_cvt_f32_u32_e32 v1, s0
	s_sub_i32 s5, 0, s0
	s_add_i32 s1, s33, 0x55f
	s_xor_b32 s4, s1, s33
	v_rcp_iflag_f32_e32 v1, v1
	s_abs_i32 s1, s1
	s_ashr_i32 s4, s4, 31
	v_mul_f32_e32 v1, 0x4f7ffffe, v1
	v_cvt_u32_f32_e32 v1, v1
	s_nop 0
	v_readfirstlane_b32 s6, v1
	s_mul_i32 s5, s5, s6
	s_mul_hi_u32 s5, s6, s5
	s_add_i32 s6, s6, s5
	s_mul_hi_u32 s5, s1, s6
	s_mul_i32 s6, s5, s0
	s_sub_i32 s1, s1, s6
	s_add_i32 s7, s5, 1
	s_sub_i32 s6, s1, s0
	s_cmp_ge_u32 s1, s0
	s_cselect_b32 s5, s7, s5
	s_cselect_b32 s1, s6, s1
	s_add_i32 s6, s5, 1
	s_cmp_ge_u32 s1, s0
	s_cselect_b32 s0, s6, s5
	s_xor_b32 s0, s0, s4
	s_sub_i32 s0, s0, s4
	s_mul_i32 s24, s0, s2
	s_add_i32 s1, s24, s0
	s_sub_i32 s4, 0x560, s24
	s_cmpk_lt_i32 s24, 0x560
	s_cselect_b32 s4, s4, 0
	s_cmpk_lt_i32 s1, 0x561
	s_cselect_b32 s25, s0, s4
	s_cbranch_execz .LBB0_79
	s_branch .LBB0_80

.LBB0_118:
	s_cmp_gt_i32 s97, 1
	s_cselect_b64 s[0:1], -1, 0
	s_and_b64 s[4:5], s[40:41], s[0:1]
	s_andn2_b64 vcc, exec, s[4:5]
	s_mov_b32 s88, s38
	s_mov_b32 s89, s39
	s_cbranch_vccnz .LBB0_172
	s_waitcnt vmcnt(0) lgkmcnt(0)
	s_barrier
	s_mov_b64 s[4:5], exec
	v_readlane_b32 s6, v254, 2
	v_readlane_b32 s7, v254, 3
	s_nop 1
	s_and_b64 s[6:7], s[4:5], s[6:7]
	s_mov_b64 exec, s[6:7]
	s_cbranch_execz .Lp0_wait_join
	v_mov_b32_e32 v1, 0x23fc4
	ds_read_b32 v2, v1
	s_add_u32 s8, s62, 0x40d800
	s_addc_u32 s9, s63, 0
	v_mov_b32_e32 v1, 0x400
	s_mov_b32 s10, 0
.Lp0_spin:
	global_load_dword v3, v1, s[8:9] sc1
	s_waitcnt vmcnt(0) lgkmcnt(0)
	v_cmp_ge_u32_e32 vcc, v3, v2
	s_cbranch_vccnz .Lp0_spin_done
	s_sleep 1
	s_add_u32 s10, s10, 1
	s_cmp_lt_u32 s10, 0x100000
	s_cbranch_scc1 .Lp0_spin

.Lp0_wait_join:
	s_mov_b64 exec, s[4:5]
	s_barrier
.LBB0_172:
	s_cmp_lt_i32 s96, 2
	s_cselect_b64 s[4:5], -1, 0
	s_lshl_b32 s54, s2, 3
	s_and_b64 s[4:5], s[4:5], s[0:1]
	s_add_i32 s44, s89, s54
	s_andn2_b64 vcc, exec, s[4:5]
	s_lshl_b32 s48, s33, 4
	s_cbranch_vccnz .LBB0_181
	s_cmpk_gt_i32 s44, 0x1fff
	s_cbranch_scc1 .LBB0_181
	v_mbcnt_lo_u32_b32 v1, -1, 0
	v_mbcnt_hi_u32_b32 v3, -1, v1
	v_and_b32_e32 v1, 64, v3
	v_add_u32_e32 v5, 64, v1
	v_xor_b32_e32 v1, 1, v3
	v_cmp_lt_i32_e32 vcc, v1, v5
	v_xor_b32_e32 v7, 2, v3
	v_readlane_b32 s0, v254, 2
	v_cndmask_b32_e32 v1, v3, v1, vcc
	v_cmp_lt_i32_e32 vcc, v7, v5
	v_lshlrev_b32_e32 v2, 3, v191
	v_readlane_b32 s1, v254, 3
	v_cndmask_b32_e32 v7, v3, v7, vcc
	v_lshlrev_b32_e32 v79, 2, v7
	v_xor_b32_e32 v7, 4, v3
	v_cmp_lt_i32_e32 vcc, v7, v5
	v_mov_b32_e32 v67, 0
	v_or_b32_e32 v6, 0x400, v2
	v_readlane_b32 s8, v254, 6
	v_cndmask_b32_e32 v7, v3, v7, vcc
	v_readlane_b32 s0, v254, 4
	v_or_b32_e32 v8, 0x600, v2
	v_readlane_b32 s22, v254, 20
	v_readlane_b32 s23, v254, 21
	v_lshlrev_b32_e32 v10, 2, v6
	v_mov_b32_e32 v11, v67
	v_lshlrev_b32_e32 v81, 2, v7
	v_xor_b32_e32 v7, 8, v3
	v_readlane_b32 s1, v254, 5
	v_lshlrev_b32_e32 v66, 5, v191
	v_lshl_add_u64 v[70:71], s[22:23], 0, v[10:11]
	v_lshlrev_b32_e32 v10, 2, v8
	v_cmp_lt_i32_e32 vcc, v7, v5
	v_lshl_add_u64 v[72:73], s[22:23], 0, v[10:11]
	v_lshl_add_u64 v[10:11], s[62:63], 0, v[66:67]
	s_mov_b64 s[0:1], 0x80000
	v_cndmask_b32_e32 v7, v3, v7, vcc
	v_readlane_b32 s21, v254, 19
	v_lshl_add_u64 v[74:75], v[10:11], 0, s[0:1]
	s_lshl_b32 s6, s44, 1
	v_lshlrev_b32_e32 v83, 2, v7
	v_xor_b32_e32 v7, 16, v3
	s_lshl_b32 s0, s2, 8
	s_lshl_b32 s1, s89, 5
	v_cmp_lt_i32_e32 vcc, v7, v5
	s_add_i32 s21, s0, s1
	s_lshl_b32 s0, s2, 14
	s_lshl_b32 s1, s89, 11
	s_ashr_i32 s7, s6, 31
	v_cndmask_b32_e32 v7, v3, v7, vcc
	s_lshl_b32 s26, s33, 8
	s_add_i32 s27, s0, s1
	s_lshl_b32 s28, s33, 14
	s_ashr_i32 s49, s48, 31
	s_lshl_b64 s[0:1], s[6:7], 12
	v_lshlrev_b32_e32 v84, 2, v7
	v_xor_b32_e32 v7, 32, v3
	s_add_u32 s0, s62, s0
	v_lshl_add_u64 v[68:69], s[22:23], 0, v[66:67]
	v_cmp_lt_i32_e32 vcc, v7, v5
	v_lshlrev_b32_e32 v66, 4, v191
	s_addc_u32 s1, s63, s1
	v_or_b32_e32 v4, 0x200, v2
	v_readlane_b32 s9, v254, 7
	v_readlane_b32 s10, v254, 8
	v_readlane_b32 s11, v254, 9
	v_readlane_b32 s12, v254, 10
	v_readlane_b32 s13, v254, 11
	v_readlane_b32 s14, v254, 12
	v_readlane_b32 s15, v254, 13
	v_readlane_b32 s16, v254, 14
	v_readlane_b32 s17, v254, 15
	v_readlane_b32 s18, v254, 16
	v_readlane_b32 s19, v254, 17
	v_readlane_b32 s20, v254, 18
	v_cndmask_b32_e32 v3, v3, v7, vcc
	v_lshl_add_u64 v[10:11], s[0:1], 0, v[66:67]
	s_mov_b64 s[0:1], 0x4800000
	s_mov_b32 s9, 0
	v_lshlrev_b32_e32 v1, 2, v1
	v_lshlrev_b32_e32 v85, 2, v3
	s_mov_b32 s34, s89
	v_lshl_add_u64 v[76:77], v[10:11], 0, s[0:1]
	s_lshl_b64 s[10:11], s[48:49], 12
	v_lshlrev_b32_e32 v66, 2, v2
	s_mov_b64 s[12:13], 0x1000
	s_movk_i32 s29, 0x1000
	s_mov_b64 s[14:15], 0x1800
	s_mov_b64 s[16:17], 0x10000
	s_mov_b32 s30, 0x10000
	s_mov_b64 s[18:19], 0x10800
	s_mov_b32 s20, 0x3a000000
	s_mov_b32 s31, 0x800000
	v_lshlrev_b32_e32 v86, 2, v4
	v_lshlrev_b32_e32 v87, 2, v6
	v_lshlrev_b32_e32 v88, 2, v8
	v_mov_b32_e32 v78, 0x358637bd
	s_branch .LBB0_176
